# phase-3 epilogue residual loads nontemporal
# speedup vs baseline: 1.0134x; 1.0134x over previous
.LBB0_998:
	v_lshl_add_u32 v146, s56, 8, v165
	v_lshl_or_b32 v142, s55, 8, v167
	v_ashrrev_i32_e32 v147, 31, v146
	v_lshlrev_b64 v[152:153], 11, v[146:147]
	v_ashrrev_i32_e32 v143, 31, v142
	v_lshl_add_u64 v[148:149], s[58:59], 0, v[152:153]
	v_lshlrev_b64 v[144:145], 1, v[142:143]
	v_lshl_add_u64 v[148:149], v[148:149], 0, v[144:145]
	global_load_dwordx2 v[186:187], v[148:149], off nt
	global_load_dwordx2 v[188:189], v[148:149], off offset:32 nt
	global_load_dwordx2 v[190:191], v[148:149], off offset:256 nt
	global_load_dwordx2 v[192:193], v[148:149], off offset:288 nt
	v_and_b32_e32 v149, 64, v184
	v_or_b32_e32 v148, 16, v146
	v_add_u32_e32 v185, 64, v149
	v_ashrrev_i32_e32 v149, 31, v148
	v_lshlrev_b64 v[150:151], 11, v[148:149]
	v_lshl_add_u64 v[152:153], s[94:95], 0, v[152:153]
	v_lshl_add_u64 v[154:155], s[58:59], 0, v[150:151]
	v_lshl_add_u64 v[194:195], v[152:153], 0, v[144:145]
	v_lshl_add_u64 v[152:153], v[154:155], 0, v[144:145]
	global_load_dwordx2 v[158:159], v[152:153], off nt
	global_load_dwordx2 v[156:157], v[152:153], off offset:32 nt
	global_load_dwordx2 v[154:155], v[152:153], off offset:256 nt
	s_nop 0
	global_load_dwordx2 v[152:153], v[152:153], off offset:288 nt
	v_xor_b32_e32 v147, 16, v184
	v_cmp_lt_i32_e32 vcc, v147, v185
	s_waitcnt vmcnt(0)
	v_lshlrev_b32_e32 v196, 16, v186
	v_and_b32_e32 v197, 0xffff0000, v186
	v_lshlrev_b32_e32 v186, 16, v187
	v_and_b32_e32 v187, 0xffff0000, v187
	v_lshlrev_b32_e32 v198, 16, v188
	v_and_b32_e32 v199, 0xffff0000, v188
	v_lshlrev_b32_e32 v188, 16, v189
	v_and_b32_e32 v189, 0xffff0000, v189
	v_lshlrev_b32_e32 v202, 16, v192
	v_and_b32_e32 v203, 0xffff0000, v192
	v_lshlrev_b32_e32 v192, 16, v193
	v_and_b32_e32 v193, 0xffff0000, v193
	v_pk_fma_f32 v[128:129], v[186:187], s[22:23], v[128:129] op_sel_hi:[1,0,1]
	v_pk_fma_f32 v[126:127], v[196:197], s[22:23], v[126:127] op_sel_hi:[1,0,1]
	v_lshlrev_b32_e32 v200, 16, v190
	v_and_b32_e32 v201, 0xffff0000, v190
	v_lshlrev_b32_e32 v190, 16, v191
	v_and_b32_e32 v191, 0xffff0000, v191
	v_pk_fma_f32 v[124:125], v[188:189], s[22:23], v[124:125] op_sel_hi:[1,0,1]
	v_pk_fma_f32 v[122:123], v[198:199], s[22:23], v[122:123] op_sel_hi:[1,0,1]
	v_pk_fma_f32 v[186:187], v[192:193], s[22:23], v[116:117] op_sel_hi:[1,0,1]
	v_pk_fma_f32 v[188:189], v[202:203], s[22:23], v[114:115] op_sel_hi:[1,0,1]
	v_cvt_pk_bf16_f32 v114, v126, v127
	v_add_f32_e32 v149, v126, v127
	v_add_f32_e32 v192, v128, v129
	v_pk_fma_f32 v[120:121], v[190:191], s[22:23], v[120:121] op_sel_hi:[1,0,1]
	v_pk_fma_f32 v[118:119], v[200:201], s[22:23], v[118:119] op_sel_hi:[1,0,1]
	v_cvt_pk_bf16_f32 v115, v128, v129
	v_add_f32_e32 v193, v122, v123
	v_add_f32_e32 v196, v124, v125
	global_store_dwordx2 v[194:195], v[114:115], off
	v_add_f32_e32 v114, v149, v192
	v_cvt_pk_bf16_f32 v116, v122, v123
	v_add_f32_e32 v197, v118, v119
	v_add_f32_e32 v198, v120, v121
	v_add_f32_e32 v115, v193, v196
	v_add_f32_e32 v114, 0, v114
	v_cvt_pk_bf16_f32 v117, v124, v125
	v_add_f32_e32 v199, v188, v189
	v_add_f32_e32 v200, v186, v187
	global_store_dwordx2 v[194:195], v[116:117], off offset:32
	v_add_f32_e32 v116, v197, v198
	v_add_f32_e32 v114, v114, v115
	v_mul_f32_e32 v127, v127, v127
	v_add_f32_e32 v117, v199, v200
	v_add_f32_e32 v114, v114, v116
	v_cndmask_b32_e32 v116, v184, v147, vcc
	v_mul_f32_e32 v129, v129, v129
	v_mul_f32_e32 v123, v123, v123
	v_mul_f32_e32 v125, v125, v125
	v_fmac_f32_e32 v127, v126, v126
	v_add_f32_e32 v114, v114, v117
	v_lshlrev_b32_e32 v126, 2, v116
	v_cvt_pk_bf16_f32 v190, v118, v119
	v_cvt_pk_bf16_f32 v191, v120, v121
	v_mul_f32_e32 v119, v119, v119
	v_mul_f32_e32 v121, v121, v121
	v_fmac_f32_e32 v129, v128, v128
	v_fmac_f32_e32 v123, v122, v122
	v_fmac_f32_e32 v125, v124, v124
	ds_bpermute_b32 v116, v126, v114
	v_mul_f32_e32 v201, v189, v189
	v_fmac_f32_e32 v119, v118, v118
	v_fmac_f32_e32 v121, v120, v120
	v_add_f32_e32 v118, v127, v129
	v_add_f32_e32 v120, v123, v125
	v_mul_f32_e32 v117, v187, v187
	v_fmac_f32_e32 v201, v188, v188
	v_add_f32_e32 v119, v119, v121
	v_add_f32_e32 v115, v118, v120
	v_fmac_f32_e32 v117, v186, v186
	v_add_f32_e32 v115, v115, v119
	v_add_f32_e32 v117, v201, v117
	v_add_f32_e32 v117, v115, v117
	s_waitcnt lgkmcnt(0)
	v_add_f32_e32 v114, v114, v116
	ds_bpermute_b32 v116, v126, v117
	v_xor_b32_e32 v115, 32, v184
	v_cmp_lt_i32_e32 vcc, v115, v185
	global_store_dwordx2 v[194:195], v[190:191], off offset:256
	v_cvt_pk_bf16_f32 v118, v188, v189
	s_waitcnt lgkmcnt(0)
	v_add_f32_e32 v116, v117, v116
	v_cndmask_b32_e32 v115, v184, v115, vcc
	v_lshlrev_b32_e32 v127, 2, v115
	ds_bpermute_b32 v115, v127, v114
	ds_bpermute_b32 v117, v127, v116
	v_cvt_pk_bf16_f32 v119, v186, v187
	global_store_dwordx2 v[194:195], v[118:119], off offset:288
	s_and_saveexec_b64 s[2:3], s[4:5]
	s_cbranch_execz .LBB0_1000
	s_waitcnt lgkmcnt(0)
	v_add_f32_e32 v116, v116, v117
	v_add_f32_e32 v117, v114, v115
	v_lshlrev_b32_e32 v114, 1, v146
	v_ashrrev_i32_e32 v115, 31, v114
	v_lshl_add_u64 v[114:115], v[114:115], 2, s[82:83]
	global_atomic_add_f32 v[114:115], v117, off
	global_atomic_add_f32 v[114:115], v116, off offset:4
.LBB0_1000:
	s_or_b64 exec, exec, s[2:3]
	v_or_b32_e32 v114, 32, v146
	s_waitcnt lgkmcnt(1)
	v_ashrrev_i32_e32 v115, 31, v114
	s_waitcnt lgkmcnt(0)
	v_lshlrev_b64 v[116:117], 11, v[114:115]
	v_lshl_add_u64 v[118:119], s[58:59], 0, v[116:117]
	v_lshl_add_u64 v[118:119], v[118:119], 0, v[144:145]
	global_load_dwordx2 v[124:125], v[118:119], off nt
	global_load_dwordx2 v[122:123], v[118:119], off offset:32 nt
	global_load_dwordx2 v[120:121], v[118:119], off offset:256 nt
	s_nop 0
	global_load_dwordx2 v[118:119], v[118:119], off offset:288 nt
	v_lshlrev_b32_e32 v128, 16, v158
	v_and_b32_e32 v129, 0xffff0000, v158
	v_lshlrev_b32_e32 v158, 16, v159
	v_and_b32_e32 v159, 0xffff0000, v159
	v_pk_fma_f32 v[110:111], v[128:129], s[22:23], v[110:111] op_sel_hi:[1,0,1]
	v_pk_fma_f32 v[112:113], v[158:159], s[22:23], v[112:113] op_sel_hi:[1,0,1]
	v_cvt_pk_bf16_f32 v128, v110, v111
	v_add_f32_e32 v115, v110, v111
	v_mul_f32_e32 v111, v111, v111
	v_lshl_add_u64 v[150:151], s[94:95], 0, v[150:151]
	v_fmac_f32_e32 v111, v110, v110
	v_mul_f32_e32 v110, v113, v113
	v_lshlrev_b32_e32 v186, 16, v156
	v_and_b32_e32 v187, 0xffff0000, v156
	v_lshl_add_u64 v[150:151], v[150:151], 0, v[144:145]
	v_fmac_f32_e32 v110, v112, v112
	v_lshlrev_b32_e32 v156, 16, v157
	v_and_b32_e32 v157, 0xffff0000, v157
	v_cvt_pk_bf16_f32 v129, v112, v113
	global_store_dwordx2 v[150:151], v[128:129], off
	v_add_f32_e32 v128, v112, v113
	v_add_f32_e32 v112, v111, v110
	v_pk_fma_f32 v[106:107], v[186:187], s[22:23], v[106:107] op_sel_hi:[1,0,1]
	v_pk_fma_f32 v[108:109], v[156:157], s[22:23], v[108:109] op_sel_hi:[1,0,1]
	v_cvt_pk_bf16_f32 v110, v106, v107
	v_lshlrev_b32_e32 v188, 16, v154
	v_cvt_pk_bf16_f32 v111, v108, v109
	global_store_dwordx2 v[150:151], v[110:111], off offset:32
	v_add_f32_e32 v110, v106, v107
	v_mul_f32_e32 v107, v107, v107
	v_and_b32_e32 v189, 0xffff0000, v154
	v_lshlrev_b32_e32 v154, 16, v155
	v_and_b32_e32 v155, 0xffff0000, v155
	v_fmac_f32_e32 v107, v106, v106
	v_mul_f32_e32 v106, v109, v109
	v_add_f32_e32 v115, v115, v128
	v_add_f32_e32 v111, v108, v109
	v_fmac_f32_e32 v106, v108, v108
	v_pk_fma_f32 v[104:105], v[154:155], s[22:23], v[104:105] op_sel_hi:[1,0,1]
	v_pk_fma_f32 v[102:103], v[188:189], s[22:23], v[102:103] op_sel_hi:[1,0,1]
	v_add_f32_e32 v115, 0, v115
	v_add_f32_e32 v110, v110, v111
	v_add_f32_e32 v106, v107, v106
	v_add_f32_e32 v107, v102, v103
	v_add_f32_e32 v108, v104, v105
	v_add_f32_e32 v110, v115, v110
	v_add_f32_e32 v107, v107, v108
	v_add_f32_e32 v110, v110, v107
	v_mul_f32_e32 v107, v103, v103
	v_mul_f32_e32 v108, v105, v105
	v_fmac_f32_e32 v107, v102, v102
	v_fmac_f32_e32 v108, v104, v104
	v_lshlrev_b32_e32 v190, 16, v152
	v_and_b32_e32 v191, 0xffff0000, v152
	v_lshlrev_b32_e32 v152, 16, v153
	v_and_b32_e32 v153, 0xffff0000, v153
	v_add_f32_e32 v106, v112, v106
	v_add_f32_e32 v107, v107, v108
	v_add_f32_e32 v111, v106, v107
	v_pk_fma_f32 v[106:107], v[152:153], s[22:23], v[100:101] op_sel_hi:[1,0,1]
	v_pk_fma_f32 v[108:109], v[190:191], s[22:23], v[98:99] op_sel_hi:[1,0,1]
	v_add_f32_e32 v99, v106, v107
	v_add_f32_e32 v98, v108, v109
	v_add_f32_e32 v98, v98, v99
	v_mul_f32_e32 v99, v109, v109
	v_mul_f32_e32 v100, v107, v107
	v_fmac_f32_e32 v99, v108, v108
	v_fmac_f32_e32 v100, v106, v106
	v_add_f32_e32 v99, v99, v100
	v_add_f32_e32 v98, v110, v98
	v_add_f32_e32 v101, v111, v99
	ds_bpermute_b32 v100, v126, v98
	ds_bpermute_b32 v110, v126, v101
	v_cvt_pk_bf16_f32 v102, v102, v103
	v_cvt_pk_bf16_f32 v103, v104, v105
	global_store_dwordx2 v[150:151], v[102:103], off offset:256
	s_waitcnt lgkmcnt(1)
	v_add_f32_e32 v98, v98, v100
	s_waitcnt lgkmcnt(0)
	v_add_f32_e32 v100, v101, v110
	ds_bpermute_b32 v99, v127, v98
	ds_bpermute_b32 v101, v127, v100
	v_cvt_pk_bf16_f32 v102, v108, v109
	v_cvt_pk_bf16_f32 v103, v106, v107
	global_store_dwordx2 v[150:151], v[102:103], off offset:288
	s_and_saveexec_b64 s[2:3], s[4:5]
	s_cbranch_execz .LBB0_1002
	s_waitcnt lgkmcnt(0)
	v_add_f32_e32 v100, v100, v101
	v_add_f32_e32 v101, v98, v99
	v_lshlrev_b32_e32 v98, 1, v148
	v_ashrrev_i32_e32 v99, 31, v98
	v_lshl_add_u64 v[98:99], v[98:99], 2, s[82:83]
	global_atomic_add_f32 v[98:99], v101, off
	global_atomic_add_f32 v[98:99], v100, off offset:4
.LBB0_1002:
	s_or_b64 exec, exec, s[2:3]
	v_or_b32_e32 v98, 48, v146
	s_waitcnt lgkmcnt(1)
	v_ashrrev_i32_e32 v99, 31, v98
	s_waitcnt lgkmcnt(0)
	v_lshlrev_b64 v[100:101], 11, v[98:99]
	v_lshl_add_u64 v[102:103], s[58:59], 0, v[100:101]
	v_lshl_add_u64 v[102:103], v[102:103], 0, v[144:145]
	global_load_dwordx2 v[108:109], v[102:103], off nt
	global_load_dwordx2 v[106:107], v[102:103], off offset:32 nt
	global_load_dwordx2 v[104:105], v[102:103], off offset:256 nt
	s_nop 0
	global_load_dwordx2 v[102:103], v[102:103], off offset:288 nt
	s_waitcnt vmcnt(11)
	v_lshlrev_b32_e32 v110, 16, v124
	v_and_b32_e32 v111, 0xffff0000, v124
	v_lshlrev_b32_e32 v112, 16, v125
	v_and_b32_e32 v113, 0xffff0000, v125
	v_pk_fma_f32 v[94:95], v[110:111], s[22:23], v[94:95] op_sel_hi:[1,0,1]
	v_pk_fma_f32 v[96:97], v[112:113], s[22:23], v[96:97] op_sel_hi:[1,0,1]
	v_cvt_pk_bf16_f32 v110, v94, v95
	v_add_f32_e32 v99, v94, v95
	v_mul_f32_e32 v95, v95, v95
	v_lshl_add_u64 v[112:113], s[94:95], 0, v[116:117]
	v_fmac_f32_e32 v95, v94, v94
	v_mul_f32_e32 v94, v97, v97
	s_waitcnt vmcnt(10)
	v_lshlrev_b32_e32 v124, 16, v122
	v_and_b32_e32 v125, 0xffff0000, v122
	v_lshl_add_u64 v[112:113], v[112:113], 0, v[144:145]
	v_fmac_f32_e32 v94, v96, v96
	v_lshlrev_b32_e32 v122, 16, v123
	v_and_b32_e32 v123, 0xffff0000, v123
	v_cvt_pk_bf16_f32 v111, v96, v97
	global_store_dwordx2 v[112:113], v[110:111], off
	v_add_f32_e32 v110, v96, v97
	v_add_f32_e32 v96, v95, v94
	v_pk_fma_f32 v[90:91], v[124:125], s[22:23], v[90:91] op_sel_hi:[1,0,1]
	v_pk_fma_f32 v[92:93], v[122:123], s[22:23], v[92:93] op_sel_hi:[1,0,1]
	v_cvt_pk_bf16_f32 v94, v90, v91
	s_waitcnt vmcnt(10)
	v_lshlrev_b32_e32 v128, 16, v120
	v_cvt_pk_bf16_f32 v95, v92, v93
	global_store_dwordx2 v[112:113], v[94:95], off offset:32
	v_add_f32_e32 v94, v90, v91
	v_mul_f32_e32 v91, v91, v91
	v_and_b32_e32 v129, 0xffff0000, v120
	v_lshlrev_b32_e32 v120, 16, v121
	v_and_b32_e32 v121, 0xffff0000, v121
	v_fmac_f32_e32 v91, v90, v90
	v_mul_f32_e32 v90, v93, v93
	v_add_f32_e32 v99, v99, v110
	v_add_f32_e32 v95, v92, v93
	v_fmac_f32_e32 v90, v92, v92
	v_pk_fma_f32 v[88:89], v[120:121], s[22:23], v[88:89] op_sel_hi:[1,0,1]
	v_pk_fma_f32 v[86:87], v[128:129], s[22:23], v[86:87] op_sel_hi:[1,0,1]
	v_add_f32_e32 v99, 0, v99
	v_add_f32_e32 v94, v94, v95
	v_add_f32_e32 v90, v91, v90
	v_add_f32_e32 v91, v86, v87
	v_add_f32_e32 v92, v88, v89
	v_add_f32_e32 v94, v99, v94
	v_add_f32_e32 v91, v91, v92
	v_add_f32_e32 v94, v94, v91
	v_mul_f32_e32 v91, v87, v87
	v_mul_f32_e32 v92, v89, v89
	v_fmac_f32_e32 v91, v86, v86
	v_fmac_f32_e32 v92, v88, v88
	s_waitcnt vmcnt(10)
	v_lshlrev_b32_e32 v148, 16, v118
	v_and_b32_e32 v149, 0xffff0000, v118
	v_lshlrev_b32_e32 v118, 16, v119
	v_and_b32_e32 v119, 0xffff0000, v119
	v_add_f32_e32 v90, v96, v90
	v_add_f32_e32 v91, v91, v92
	v_add_f32_e32 v95, v90, v91
	v_pk_fma_f32 v[90:91], v[118:119], s[22:23], v[84:85] op_sel_hi:[1,0,1]
	v_pk_fma_f32 v[92:93], v[148:149], s[22:23], v[82:83] op_sel_hi:[1,0,1]
	v_add_f32_e32 v83, v90, v91
	v_add_f32_e32 v82, v92, v93
	v_add_f32_e32 v82, v82, v83
	v_mul_f32_e32 v83, v93, v93
	v_mul_f32_e32 v84, v91, v91
	v_fmac_f32_e32 v83, v92, v92
	v_fmac_f32_e32 v84, v90, v90
	v_add_f32_e32 v83, v83, v84
	v_add_f32_e32 v82, v94, v82
	v_add_f32_e32 v85, v95, v83
	ds_bpermute_b32 v84, v126, v82
	ds_bpermute_b32 v94, v126, v85
	v_cvt_pk_bf16_f32 v86, v86, v87
	v_cvt_pk_bf16_f32 v87, v88, v89
	global_store_dwordx2 v[112:113], v[86:87], off offset:256
	s_waitcnt lgkmcnt(1)
	v_add_f32_e32 v82, v82, v84
	s_waitcnt lgkmcnt(0)
	v_add_f32_e32 v84, v85, v94
	ds_bpermute_b32 v83, v127, v82
	ds_bpermute_b32 v85, v127, v84
	v_cvt_pk_bf16_f32 v86, v92, v93
	v_cvt_pk_bf16_f32 v87, v90, v91
	global_store_dwordx2 v[112:113], v[86:87], off offset:288
	s_and_saveexec_b64 s[2:3], s[4:5]
	s_cbranch_execz .LBB0_1004
	s_waitcnt lgkmcnt(0)
	v_add_f32_e32 v84, v84, v85
	v_add_f32_e32 v85, v82, v83
	v_lshlrev_b32_e32 v82, 1, v114
	v_ashrrev_i32_e32 v83, 31, v82
	v_lshl_add_u64 v[82:83], v[82:83], 2, s[82:83]
	global_atomic_add_f32 v[82:83], v85, off
	global_atomic_add_f32 v[82:83], v84, off offset:4
.LBB0_1004:
	s_or_b64 exec, exec, s[2:3]
	v_add_u32_e32 v82, 0x80, v146
	s_waitcnt lgkmcnt(1)
	v_ashrrev_i32_e32 v83, 31, v82
	s_waitcnt lgkmcnt(0)
	v_lshlrev_b64 v[84:85], 11, v[82:83]
	v_lshl_add_u64 v[86:87], s[58:59], 0, v[84:85]
	v_lshl_add_u64 v[86:87], v[86:87], 0, v[144:145]
	global_load_dwordx2 v[92:93], v[86:87], off nt
	global_load_dwordx2 v[90:91], v[86:87], off offset:32 nt
	global_load_dwordx2 v[88:89], v[86:87], off offset:256 nt
	s_nop 0
	global_load_dwordx2 v[86:87], v[86:87], off offset:288 nt
	s_waitcnt vmcnt(11)
	v_lshlrev_b32_e32 v94, 16, v108
	v_and_b32_e32 v95, 0xffff0000, v108
	v_lshlrev_b32_e32 v96, 16, v109
	v_and_b32_e32 v97, 0xffff0000, v109
	v_pk_fma_f32 v[78:79], v[94:95], s[22:23], v[78:79] op_sel_hi:[1,0,1]
	v_pk_fma_f32 v[80:81], v[96:97], s[22:23], v[80:81] op_sel_hi:[1,0,1]
	v_cvt_pk_bf16_f32 v94, v78, v79
	v_add_f32_e32 v83, v78, v79
	v_mul_f32_e32 v79, v79, v79
	v_lshl_add_u64 v[96:97], s[94:95], 0, v[100:101]
	v_fmac_f32_e32 v79, v78, v78
	v_mul_f32_e32 v78, v81, v81
	s_waitcnt vmcnt(10)
	v_lshlrev_b32_e32 v108, 16, v106
	v_and_b32_e32 v109, 0xffff0000, v106
	v_lshl_add_u64 v[96:97], v[96:97], 0, v[144:145]
	v_fmac_f32_e32 v78, v80, v80
	v_lshlrev_b32_e32 v106, 16, v107
	v_and_b32_e32 v107, 0xffff0000, v107
	v_cvt_pk_bf16_f32 v95, v80, v81
	global_store_dwordx2 v[96:97], v[94:95], off
	v_add_f32_e32 v94, v80, v81
	v_add_f32_e32 v80, v79, v78
	v_pk_fma_f32 v[74:75], v[108:109], s[22:23], v[74:75] op_sel_hi:[1,0,1]
	v_pk_fma_f32 v[76:77], v[106:107], s[22:23], v[76:77] op_sel_hi:[1,0,1]
	v_cvt_pk_bf16_f32 v78, v74, v75
	s_waitcnt vmcnt(10)
	v_lshlrev_b32_e32 v110, 16, v104
	v_cvt_pk_bf16_f32 v79, v76, v77
	global_store_dwordx2 v[96:97], v[78:79], off offset:32
	v_add_f32_e32 v78, v74, v75
	v_mul_f32_e32 v75, v75, v75
	v_and_b32_e32 v111, 0xffff0000, v104
	v_lshlrev_b32_e32 v104, 16, v105
	v_and_b32_e32 v105, 0xffff0000, v105
	v_fmac_f32_e32 v75, v74, v74
	v_mul_f32_e32 v74, v77, v77
	v_add_f32_e32 v83, v83, v94
	v_add_f32_e32 v79, v76, v77
	v_fmac_f32_e32 v74, v76, v76
	v_pk_fma_f32 v[72:73], v[104:105], s[22:23], v[72:73] op_sel_hi:[1,0,1]
	v_pk_fma_f32 v[70:71], v[110:111], s[22:23], v[70:71] op_sel_hi:[1,0,1]
	v_add_f32_e32 v83, 0, v83
	v_add_f32_e32 v78, v78, v79
	v_add_f32_e32 v74, v75, v74
	v_add_f32_e32 v75, v70, v71
	v_add_f32_e32 v76, v72, v73
	v_add_f32_e32 v78, v83, v78
	v_add_f32_e32 v75, v75, v76
	v_add_f32_e32 v78, v78, v75
	v_mul_f32_e32 v75, v71, v71
	v_mul_f32_e32 v76, v73, v73
	v_fmac_f32_e32 v75, v70, v70
	v_fmac_f32_e32 v76, v72, v72
	s_waitcnt vmcnt(10)
	v_lshlrev_b32_e32 v112, 16, v102
	v_and_b32_e32 v113, 0xffff0000, v102
	v_lshlrev_b32_e32 v102, 16, v103
	v_and_b32_e32 v103, 0xffff0000, v103
	v_add_f32_e32 v74, v80, v74
	v_add_f32_e32 v75, v75, v76
	v_add_f32_e32 v79, v74, v75
	v_pk_fma_f32 v[74:75], v[102:103], s[22:23], v[68:69] op_sel_hi:[1,0,1]
	v_pk_fma_f32 v[76:77], v[112:113], s[22:23], v[66:67] op_sel_hi:[1,0,1]
	v_add_f32_e32 v67, v74, v75
	v_add_f32_e32 v66, v76, v77
	v_add_f32_e32 v66, v66, v67
	v_mul_f32_e32 v67, v77, v77
	v_mul_f32_e32 v68, v75, v75
	v_fmac_f32_e32 v67, v76, v76
	v_fmac_f32_e32 v68, v74, v74
	v_add_f32_e32 v67, v67, v68
	v_add_f32_e32 v66, v78, v66
	v_add_f32_e32 v69, v79, v67
	ds_bpermute_b32 v68, v126, v66
	ds_bpermute_b32 v78, v126, v69
	v_cvt_pk_bf16_f32 v70, v70, v71
	v_cvt_pk_bf16_f32 v71, v72, v73
	global_store_dwordx2 v[96:97], v[70:71], off offset:256
	s_waitcnt lgkmcnt(1)
	v_add_f32_e32 v66, v66, v68
	s_waitcnt lgkmcnt(0)
	v_add_f32_e32 v68, v69, v78
	ds_bpermute_b32 v67, v127, v66
	ds_bpermute_b32 v69, v127, v68
	v_cvt_pk_bf16_f32 v70, v76, v77
	v_cvt_pk_bf16_f32 v71, v74, v75
	global_store_dwordx2 v[96:97], v[70:71], off offset:288
	s_and_saveexec_b64 s[2:3], s[4:5]
	s_cbranch_execz .LBB0_1006
	s_waitcnt lgkmcnt(0)
	v_add_f32_e32 v68, v68, v69
	v_add_f32_e32 v69, v66, v67
	v_lshlrev_b32_e32 v66, 1, v98
	v_ashrrev_i32_e32 v67, 31, v66
	v_lshl_add_u64 v[66:67], v[66:67], 2, s[82:83]
	global_atomic_add_f32 v[66:67], v69, off
	global_atomic_add_f32 v[66:67], v68, off offset:4
.LBB0_1006:
	s_or_b64 exec, exec, s[2:3]
	v_or_b32_e32 v66, 16, v82
	s_waitcnt lgkmcnt(1)
	v_ashrrev_i32_e32 v67, 31, v66
	s_waitcnt lgkmcnt(0)
	v_lshlrev_b64 v[68:69], 11, v[66:67]
	v_lshl_add_u64 v[70:71], s[58:59], 0, v[68:69]
	v_lshl_add_u64 v[70:71], v[70:71], 0, v[144:145]
	global_load_dwordx2 v[76:77], v[70:71], off nt
	global_load_dwordx2 v[74:75], v[70:71], off offset:32 nt
	global_load_dwordx2 v[72:73], v[70:71], off offset:256 nt
	s_nop 0
	global_load_dwordx2 v[70:71], v[70:71], off offset:288 nt
	s_waitcnt vmcnt(11)
	v_lshlrev_b32_e32 v78, 16, v92
	v_and_b32_e32 v79, 0xffff0000, v92
	v_lshlrev_b32_e32 v80, 16, v93
	v_and_b32_e32 v81, 0xffff0000, v93
	v_pk_fma_f32 v[62:63], v[78:79], s[22:23], v[62:63] op_sel_hi:[1,0,1]
	v_pk_fma_f32 v[64:65], v[80:81], s[22:23], v[64:65] op_sel_hi:[1,0,1]
	v_cvt_pk_bf16_f32 v78, v62, v63
	v_add_f32_e32 v67, v62, v63
	v_mul_f32_e32 v63, v63, v63
	v_lshl_add_u64 v[80:81], s[94:95], 0, v[84:85]
	v_fmac_f32_e32 v63, v62, v62
	v_mul_f32_e32 v62, v65, v65
	s_waitcnt vmcnt(10)
	v_lshlrev_b32_e32 v92, 16, v90
	v_and_b32_e32 v93, 0xffff0000, v90
	v_lshl_add_u64 v[80:81], v[80:81], 0, v[144:145]
	v_fmac_f32_e32 v62, v64, v64
	v_lshlrev_b32_e32 v90, 16, v91
	v_and_b32_e32 v91, 0xffff0000, v91
	v_cvt_pk_bf16_f32 v79, v64, v65
	global_store_dwordx2 v[80:81], v[78:79], off
	v_add_f32_e32 v78, v64, v65
	v_add_f32_e32 v64, v63, v62
	v_pk_fma_f32 v[58:59], v[92:93], s[22:23], v[58:59] op_sel_hi:[1,0,1]
	v_pk_fma_f32 v[60:61], v[90:91], s[22:23], v[60:61] op_sel_hi:[1,0,1]
	v_cvt_pk_bf16_f32 v62, v58, v59
	s_waitcnt vmcnt(10)
	v_lshlrev_b32_e32 v94, 16, v88
	v_cvt_pk_bf16_f32 v63, v60, v61
	global_store_dwordx2 v[80:81], v[62:63], off offset:32
	v_add_f32_e32 v62, v58, v59
	v_mul_f32_e32 v59, v59, v59
	v_and_b32_e32 v95, 0xffff0000, v88
	v_lshlrev_b32_e32 v88, 16, v89
	v_and_b32_e32 v89, 0xffff0000, v89
	v_fmac_f32_e32 v59, v58, v58
	v_mul_f32_e32 v58, v61, v61
	v_add_f32_e32 v67, v67, v78
	v_add_f32_e32 v63, v60, v61
	v_fmac_f32_e32 v58, v60, v60
	v_pk_fma_f32 v[56:57], v[88:89], s[22:23], v[56:57] op_sel_hi:[1,0,1]
	v_pk_fma_f32 v[54:55], v[94:95], s[22:23], v[54:55] op_sel_hi:[1,0,1]
	v_add_f32_e32 v67, 0, v67
	v_add_f32_e32 v62, v62, v63
	v_add_f32_e32 v58, v59, v58
	v_add_f32_e32 v59, v54, v55
	v_add_f32_e32 v60, v56, v57
	v_add_f32_e32 v62, v67, v62
	v_add_f32_e32 v59, v59, v60
	v_add_f32_e32 v62, v62, v59
	v_mul_f32_e32 v59, v55, v55
	v_mul_f32_e32 v60, v57, v57
	v_fmac_f32_e32 v59, v54, v54
	v_fmac_f32_e32 v60, v56, v56
	s_waitcnt vmcnt(10)
	v_lshlrev_b32_e32 v96, 16, v86
	v_and_b32_e32 v97, 0xffff0000, v86
	v_lshlrev_b32_e32 v86, 16, v87
	v_and_b32_e32 v87, 0xffff0000, v87
	v_add_f32_e32 v58, v64, v58
	v_add_f32_e32 v59, v59, v60
	v_add_f32_e32 v63, v58, v59
	v_pk_fma_f32 v[58:59], v[86:87], s[22:23], v[52:53] op_sel_hi:[1,0,1]
	v_pk_fma_f32 v[60:61], v[96:97], s[22:23], v[50:51] op_sel_hi:[1,0,1]
	v_add_f32_e32 v51, v58, v59
	v_add_f32_e32 v50, v60, v61
	v_add_f32_e32 v50, v50, v51
	v_mul_f32_e32 v51, v61, v61
	v_mul_f32_e32 v52, v59, v59
	v_fmac_f32_e32 v51, v60, v60
	v_fmac_f32_e32 v52, v58, v58
	v_add_f32_e32 v51, v51, v52
	v_add_f32_e32 v50, v62, v50
	v_add_f32_e32 v53, v63, v51
	ds_bpermute_b32 v52, v126, v50
	ds_bpermute_b32 v62, v126, v53
	v_cvt_pk_bf16_f32 v54, v54, v55
	v_cvt_pk_bf16_f32 v55, v56, v57
	global_store_dwordx2 v[80:81], v[54:55], off offset:256
	s_waitcnt lgkmcnt(1)
	v_add_f32_e32 v50, v50, v52
	s_waitcnt lgkmcnt(0)
	v_add_f32_e32 v52, v53, v62
	ds_bpermute_b32 v51, v127, v50
	ds_bpermute_b32 v53, v127, v52
	v_cvt_pk_bf16_f32 v54, v60, v61
	v_cvt_pk_bf16_f32 v55, v58, v59
	global_store_dwordx2 v[80:81], v[54:55], off offset:288
	s_and_saveexec_b64 s[2:3], s[4:5]
	s_cbranch_execz .LBB0_1008
	s_waitcnt lgkmcnt(0)
	v_add_f32_e32 v52, v52, v53
	v_add_f32_e32 v53, v50, v51
	v_lshlrev_b32_e32 v50, 1, v82
	v_ashrrev_i32_e32 v51, 31, v50
	v_lshl_add_u64 v[50:51], v[50:51], 2, s[82:83]
	global_atomic_add_f32 v[50:51], v53, off
	global_atomic_add_f32 v[50:51], v52, off offset:4
.LBB0_1008:
	s_or_b64 exec, exec, s[2:3]
	v_or_b32_e32 v50, 32, v82
	s_waitcnt lgkmcnt(1)
	v_ashrrev_i32_e32 v51, 31, v50
	s_waitcnt lgkmcnt(0)
	v_lshlrev_b64 v[52:53], 11, v[50:51]
	v_lshl_add_u64 v[54:55], s[58:59], 0, v[52:53]
	v_lshl_add_u64 v[54:55], v[54:55], 0, v[144:145]
	global_load_dwordx2 v[60:61], v[54:55], off nt
	global_load_dwordx2 v[58:59], v[54:55], off offset:32 nt
	global_load_dwordx2 v[56:57], v[54:55], off offset:256 nt
	s_nop 0
	global_load_dwordx2 v[54:55], v[54:55], off offset:288 nt
	s_waitcnt vmcnt(11)
	v_lshlrev_b32_e32 v62, 16, v76
	v_and_b32_e32 v63, 0xffff0000, v76
	v_lshlrev_b32_e32 v64, 16, v77
	v_and_b32_e32 v65, 0xffff0000, v77
	v_pk_fma_f32 v[46:47], v[62:63], s[22:23], v[46:47] op_sel_hi:[1,0,1]
	v_pk_fma_f32 v[48:49], v[64:65], s[22:23], v[48:49] op_sel_hi:[1,0,1]
	v_cvt_pk_bf16_f32 v62, v46, v47
	v_add_f32_e32 v51, v46, v47
	v_mul_f32_e32 v47, v47, v47
	v_lshl_add_u64 v[64:65], s[94:95], 0, v[68:69]
	v_fmac_f32_e32 v47, v46, v46
	v_mul_f32_e32 v46, v49, v49
	s_waitcnt vmcnt(10)
	v_lshlrev_b32_e32 v76, 16, v74
	v_and_b32_e32 v77, 0xffff0000, v74
	v_lshl_add_u64 v[64:65], v[64:65], 0, v[144:145]
	v_fmac_f32_e32 v46, v48, v48
	v_lshlrev_b32_e32 v74, 16, v75
	v_and_b32_e32 v75, 0xffff0000, v75
	v_cvt_pk_bf16_f32 v63, v48, v49
	global_store_dwordx2 v[64:65], v[62:63], off
	v_add_f32_e32 v62, v48, v49
	v_add_f32_e32 v48, v47, v46
	v_pk_fma_f32 v[42:43], v[76:77], s[22:23], v[42:43] op_sel_hi:[1,0,1]
	v_pk_fma_f32 v[44:45], v[74:75], s[22:23], v[44:45] op_sel_hi:[1,0,1]
	v_cvt_pk_bf16_f32 v46, v42, v43
	s_waitcnt vmcnt(10)
	v_lshlrev_b32_e32 v78, 16, v72
	v_cvt_pk_bf16_f32 v47, v44, v45
	global_store_dwordx2 v[64:65], v[46:47], off offset:32
	v_add_f32_e32 v46, v42, v43
	v_mul_f32_e32 v43, v43, v43
	v_and_b32_e32 v79, 0xffff0000, v72
	v_lshlrev_b32_e32 v72, 16, v73
	v_and_b32_e32 v73, 0xffff0000, v73
	v_fmac_f32_e32 v43, v42, v42
	v_mul_f32_e32 v42, v45, v45
	v_add_f32_e32 v51, v51, v62
	v_add_f32_e32 v47, v44, v45
	v_fmac_f32_e32 v42, v44, v44
	v_pk_fma_f32 v[40:41], v[72:73], s[22:23], v[40:41] op_sel_hi:[1,0,1]
	v_pk_fma_f32 v[38:39], v[78:79], s[22:23], v[38:39] op_sel_hi:[1,0,1]
	v_add_f32_e32 v51, 0, v51
	v_add_f32_e32 v46, v46, v47
	v_add_f32_e32 v42, v43, v42
	v_add_f32_e32 v43, v38, v39
	v_add_f32_e32 v44, v40, v41
	v_add_f32_e32 v46, v51, v46
	v_add_f32_e32 v43, v43, v44
	v_add_f32_e32 v46, v46, v43
	v_mul_f32_e32 v43, v39, v39
	v_mul_f32_e32 v44, v41, v41
	v_fmac_f32_e32 v43, v38, v38
	v_fmac_f32_e32 v44, v40, v40
	s_waitcnt vmcnt(10)
	v_lshlrev_b32_e32 v80, 16, v70
	v_and_b32_e32 v81, 0xffff0000, v70
	v_lshlrev_b32_e32 v70, 16, v71
	v_and_b32_e32 v71, 0xffff0000, v71
	v_add_f32_e32 v42, v48, v42
	v_add_f32_e32 v43, v43, v44
	v_add_f32_e32 v47, v42, v43
	v_pk_fma_f32 v[42:43], v[70:71], s[22:23], v[36:37] op_sel_hi:[1,0,1]
	v_pk_fma_f32 v[44:45], v[80:81], s[22:23], v[34:35] op_sel_hi:[1,0,1]
	v_add_f32_e32 v35, v42, v43
	v_add_f32_e32 v34, v44, v45
	v_add_f32_e32 v34, v34, v35
	v_mul_f32_e32 v35, v45, v45
	v_mul_f32_e32 v36, v43, v43
	v_fmac_f32_e32 v35, v44, v44
	v_fmac_f32_e32 v36, v42, v42
	v_add_f32_e32 v35, v35, v36
	v_add_f32_e32 v34, v46, v34
	v_add_f32_e32 v37, v47, v35
	ds_bpermute_b32 v36, v126, v34
	ds_bpermute_b32 v46, v126, v37
	v_cvt_pk_bf16_f32 v38, v38, v39
	v_cvt_pk_bf16_f32 v39, v40, v41
	global_store_dwordx2 v[64:65], v[38:39], off offset:256
	s_waitcnt lgkmcnt(1)
	v_add_f32_e32 v34, v34, v36
	s_waitcnt lgkmcnt(0)
	v_add_f32_e32 v36, v37, v46
	ds_bpermute_b32 v35, v127, v34
	ds_bpermute_b32 v37, v127, v36
	v_cvt_pk_bf16_f32 v38, v44, v45
	v_cvt_pk_bf16_f32 v39, v42, v43
	global_store_dwordx2 v[64:65], v[38:39], off offset:288
	s_and_saveexec_b64 s[2:3], s[4:5]
	s_cbranch_execz .LBB0_1010
	s_waitcnt lgkmcnt(0)
	v_add_f32_e32 v36, v36, v37
	v_add_f32_e32 v37, v34, v35
	v_lshlrev_b32_e32 v34, 1, v66
	v_ashrrev_i32_e32 v35, 31, v34
	v_lshl_add_u64 v[34:35], v[34:35], 2, s[82:83]
	global_atomic_add_f32 v[34:35], v37, off
	global_atomic_add_f32 v[34:35], v36, off offset:4
.LBB0_1010:
	s_or_b64 exec, exec, s[2:3]
	v_or_b32_e32 v34, 48, v82
	s_waitcnt lgkmcnt(1)
	v_ashrrev_i32_e32 v35, 31, v34
	s_waitcnt lgkmcnt(0)
	v_lshlrev_b64 v[36:37], 11, v[34:35]
	v_lshl_add_u64 v[38:39], s[58:59], 0, v[36:37]
	v_lshl_add_u64 v[38:39], v[38:39], 0, v[144:145]
	global_load_dwordx2 v[44:45], v[38:39], off nt
	global_load_dwordx2 v[42:43], v[38:39], off offset:32 nt
	global_load_dwordx2 v[40:41], v[38:39], off offset:256 nt
	s_nop 0
	global_load_dwordx2 v[38:39], v[38:39], off offset:288 nt
	s_waitcnt vmcnt(11)
	v_lshlrev_b32_e32 v46, 16, v60
	v_and_b32_e32 v47, 0xffff0000, v60
	v_lshlrev_b32_e32 v48, 16, v61
	v_and_b32_e32 v49, 0xffff0000, v61
	v_pk_fma_f32 v[30:31], v[46:47], s[22:23], v[30:31] op_sel_hi:[1,0,1]
	v_pk_fma_f32 v[32:33], v[48:49], s[22:23], v[32:33] op_sel_hi:[1,0,1]
	v_cvt_pk_bf16_f32 v46, v30, v31
	v_add_f32_e32 v35, v30, v31
	v_mul_f32_e32 v31, v31, v31
	v_lshl_add_u64 v[48:49], s[94:95], 0, v[52:53]
	v_fmac_f32_e32 v31, v30, v30
	v_mul_f32_e32 v30, v33, v33
	s_waitcnt vmcnt(10)
	v_lshlrev_b32_e32 v60, 16, v58
	v_and_b32_e32 v61, 0xffff0000, v58
	v_lshl_add_u64 v[48:49], v[48:49], 0, v[144:145]
	v_fmac_f32_e32 v30, v32, v32
	v_lshlrev_b32_e32 v58, 16, v59
	v_and_b32_e32 v59, 0xffff0000, v59
	v_cvt_pk_bf16_f32 v47, v32, v33
	global_store_dwordx2 v[48:49], v[46:47], off
	v_add_f32_e32 v46, v32, v33
	v_add_f32_e32 v32, v31, v30
	v_pk_fma_f32 v[26:27], v[60:61], s[22:23], v[26:27] op_sel_hi:[1,0,1]
	v_pk_fma_f32 v[28:29], v[58:59], s[22:23], v[28:29] op_sel_hi:[1,0,1]
	v_cvt_pk_bf16_f32 v30, v26, v27
	s_waitcnt vmcnt(10)
	v_lshlrev_b32_e32 v62, 16, v56
	v_cvt_pk_bf16_f32 v31, v28, v29
	global_store_dwordx2 v[48:49], v[30:31], off offset:32
	v_add_f32_e32 v30, v26, v27
	v_mul_f32_e32 v27, v27, v27
	v_and_b32_e32 v63, 0xffff0000, v56
	v_lshlrev_b32_e32 v56, 16, v57
	v_and_b32_e32 v57, 0xffff0000, v57
	v_fmac_f32_e32 v27, v26, v26
	v_mul_f32_e32 v26, v29, v29
	v_add_f32_e32 v35, v35, v46
	v_add_f32_e32 v31, v28, v29
	v_fmac_f32_e32 v26, v28, v28
	v_pk_fma_f32 v[24:25], v[56:57], s[22:23], v[24:25] op_sel_hi:[1,0,1]
	v_pk_fma_f32 v[22:23], v[62:63], s[22:23], v[22:23] op_sel_hi:[1,0,1]
	v_add_f32_e32 v35, 0, v35
	v_add_f32_e32 v30, v30, v31
	v_add_f32_e32 v26, v27, v26
	v_add_f32_e32 v27, v22, v23
	v_add_f32_e32 v28, v24, v25
	v_add_f32_e32 v30, v35, v30
	v_add_f32_e32 v27, v27, v28
	v_add_f32_e32 v30, v30, v27
	v_mul_f32_e32 v27, v23, v23
	v_mul_f32_e32 v28, v25, v25
	v_fmac_f32_e32 v27, v22, v22
	v_fmac_f32_e32 v28, v24, v24
	s_waitcnt vmcnt(10)
	v_lshlrev_b32_e32 v64, 16, v54
	v_and_b32_e32 v65, 0xffff0000, v54
	v_lshlrev_b32_e32 v54, 16, v55
	v_and_b32_e32 v55, 0xffff0000, v55
	v_add_f32_e32 v26, v32, v26
	v_add_f32_e32 v27, v27, v28
	v_add_f32_e32 v31, v26, v27
	v_pk_fma_f32 v[26:27], v[54:55], s[22:23], v[20:21] op_sel_hi:[1,0,1]
	v_pk_fma_f32 v[28:29], v[64:65], s[22:23], v[18:19] op_sel_hi:[1,0,1]
	v_add_f32_e32 v19, v26, v27
	v_add_f32_e32 v18, v28, v29
	v_add_f32_e32 v18, v18, v19
	v_mul_f32_e32 v19, v29, v29
	v_mul_f32_e32 v20, v27, v27
	v_fmac_f32_e32 v19, v28, v28
	v_fmac_f32_e32 v20, v26, v26
	v_add_f32_e32 v19, v19, v20
	v_add_f32_e32 v18, v30, v18
	v_add_f32_e32 v21, v31, v19
	ds_bpermute_b32 v20, v126, v18
	ds_bpermute_b32 v30, v126, v21
	v_cvt_pk_bf16_f32 v22, v22, v23
	v_cvt_pk_bf16_f32 v23, v24, v25
	global_store_dwordx2 v[48:49], v[22:23], off offset:256
	s_waitcnt lgkmcnt(1)
	v_add_f32_e32 v18, v18, v20
	s_waitcnt lgkmcnt(0)
	v_add_f32_e32 v20, v21, v30
	ds_bpermute_b32 v19, v127, v18
	ds_bpermute_b32 v21, v127, v20
	v_cvt_pk_bf16_f32 v22, v28, v29
	v_cvt_pk_bf16_f32 v23, v26, v27
	global_store_dwordx2 v[48:49], v[22:23], off offset:288
	s_and_saveexec_b64 s[2:3], s[4:5]
	s_cbranch_execz .LBB0_1012
	s_waitcnt lgkmcnt(0)
	v_add_f32_e32 v20, v20, v21
	v_add_f32_e32 v21, v18, v19
	v_lshlrev_b32_e32 v18, 1, v50
	v_ashrrev_i32_e32 v19, 31, v18
	v_lshl_add_u64 v[18:19], v[18:19], 2, s[82:83]
	global_atomic_add_f32 v[18:19], v21, off
	global_atomic_add_f32 v[18:19], v20, off offset:4
